# conv pointwise projection hand-written on the same scheme (bias as MFMA C operand, silu(gate) in the row-per-lane epilogue); compiled gemm_mid loop no longer executed
# speedup vs baseline: 1.0226x; 1.0062x over previous
.Lq_done:
	s_waitcnt vmcnt(0)
	v_mov_b32_e32 v0, v143
	s_and_b64 vcc, exec, s[72:73]
	v_and_b32_e32 v250, 31, v143
	v_bfe_u32 v251, v143, 5, 1
	v_lshrrev_b32_e32 v252, 6, v143
	v_lshl_add_u32 v252, v252, 5, v250
	v_lshlrev_b32_e32 v249, 4, v251
	v_lshlrev_b32_e32 v242, 9, v252
	v_lshl_add_u32 v242, v251, 4, v242
	v_mul_u32_u24_e32 v243, 0x1440, v252
	v_lshl_add_u32 v243, v251, 5, v243
	v_lshlrev_b32_e32 v244, 11, v252
	v_lshl_add_u32 v244, v251, 5, v244
	v_lshrrev_b32_e32 v245, 5, v143
	v_mul_u32_u24_e32 v245, 528, v245
	v_and_b32_e32 v246, 31, v143
	v_lshl_add_u32 v245, v246, 4, v245
	v_lshlrev_b32_e32 v246, 4, v143
	v_add_u32_e32 v247, 0x2000, v246
	v_mul_u32_u24_e32 v248, 528, v250
	v_lshl_add_u32 v248, v251, 4, v248
	s_cmp_lg_u64 s[90:91], 0
	s_movk_i32 s0, 136
	s_cselect_b32 s7, 128, s0
	s_lshl_b32 s7, s7, 3
	v_readlane_b32 s0, v253, 0
	s_and_b32 s1, s0, 7
	s_lshl_b32 s1, s1, 5
	s_lshr_b32 s0, s0, 3
	s_add_u32 s0, s0, s1
	s_mul_i32 s4, s0, s7
	s_lshr_b32 s4, s4, 8
	s_add_u32 s0, s0, 1
	s_mul_i32 s5, s0, s7
	s_lshr_b32 s5, s5, 8
	s_lshl_b32 s0, s74, 17
	s_add_u32 s0, s0, 0xc00000
	s_add_u32 s8, s50, s0
	s_addc_u32 s9, s51, 0
	s_lshl_b32 s0, s74, 10
	s_add_u32 s22, s42, s0
	s_addc_u32 s23, s43, 0
	s_mov_b32 s65, 0xbfb8aa3b
	s_lshr_b32 s6, s4, 3
	s_add_u32 s6, s6, 1
	s_lshl_b32 s6, s6, 3
	s_min_u32 s6, s6, s5
	s_lshr_b32 s17, s4, 3
	s_lshl_b32 s17, s17, 8
	s_lshl_b32 s54, s17, 9
	s_add_u32 s54, s54, 0x1995d000
	s_add_u32 s26, s50, s54
	s_addc_u32 s27, s51, 0
	global_load_dwordx4 v[48:51], v242, s[26:27] offset:0
	global_load_dwordx4 v[52:55], v242, s[26:27] offset:32
	global_load_dwordx4 v[56:59], v242, s[26:27] offset:64
	global_load_dwordx4 v[60:63], v242, s[26:27] offset:96
	global_load_dwordx4 v[64:67], v242, s[26:27] offset:128
	global_load_dwordx4 v[68:71], v242, s[26:27] offset:160
	global_load_dwordx4 v[72:75], v242, s[26:27] offset:192
	global_load_dwordx4 v[76:79], v242, s[26:27] offset:224
	global_load_dwordx4 v[96:99], v242, s[26:27] offset:256
	global_load_dwordx4 v[100:103], v242, s[26:27] offset:288
	global_load_dwordx4 v[104:107], v242, s[26:27] offset:320
	global_load_dwordx4 v[108:111], v242, s[26:27] offset:352
	global_load_dwordx4 v[112:115], v242, s[26:27] offset:384
	global_load_dwordx4 v[116:119], v242, s[26:27] offset:416
	global_load_dwordx4 v[120:123], v242, s[26:27] offset:448
	global_load_dwordx4 v[124:127], v242, s[26:27] offset:480
	s_mov_b32 s25, s4
	s_add_u32 s0, s5, -1
	s_min_u32 s0, s25, s0
	s_and_b32 s0, s0, 7
	s_lshl_b32 s0, s0, 14
	s_add_u32 s10, s8, s0
	s_addc_u32 s11, s9, 0
	global_load_dwordx4 v[220:223], v246, s[10:11]
	global_load_dwordx4 v[224:227], v247, s[10:11]
	s_add_u32 s25, s25, 1
	s_add_u32 s0, s5, -1
	s_min_u32 s0, s25, s0
	s_and_b32 s0, s0, 7
	s_lshl_b32 s0, s0, 14
	s_add_u32 s10, s8, s0
	s_addc_u32 s11, s9, 0
	global_load_dwordx4 v[228:231], v246, s[10:11]
	global_load_dwordx4 v[238:241], v247, s[10:11]
	s_add_u32 s25, s25, 1
	s_waitcnt vmcnt(0)
	ds_write_b128 v245, v[220:223]
	ds_write_b128 v245, v[224:227] offset:8448
	s_add_u32 s0, s5, -1
	s_min_u32 s0, s25, s0
	s_and_b32 s0, s0, 7
	s_lshl_b32 s0, s0, 14
	s_add_u32 s10, s8, s0
	s_addc_u32 s11, s9, 0
	global_load_dwordx4 v[220:223], v246, s[10:11]
	global_load_dwordx4 v[224:227], v247, s[10:11]
	s_add_u32 s25, s25, 1
	s_add_u32 s0, s4, 0
	s_and_b32 s0, s0, 7
	s_lshl_b32 s0, s0, 7
	s_add_u32 s30, s22, s0
	s_addc_u32 s31, s23, 0
	global_load_dwordx4 v[144:147], v249, s[30:31] offset:0
	global_load_dwordx4 v[148:151], v249, s[30:31] offset:32
	global_load_dwordx4 v[152:155], v249, s[30:31] offset:64
	global_load_dwordx4 v[156:159], v249, s[30:31] offset:96
	global_load_dword v179, v249, s[22:23]
	global_load_dword v128, v249, s[22:23]
	global_load_dword v179, v249, s[22:23]
	global_load_dword v128, v249, s[22:23]
	s_waitcnt lgkmcnt(0)
	s_barrier
	s_mov_b32 s16, 0
.Lc_loop:
	s_waitcnt vmcnt(18)
	ds_write_b128 v245, v[228:231] offset:16896
	ds_write_b128 v245, v[238:241] offset:25344
	s_add_u32 s0, s5, -1
	s_min_u32 s0, s25, s0
	s_and_b32 s0, s0, 7
	s_lshl_b32 s0, s0, 14
	s_add_u32 s10, s8, s0
	s_addc_u32 s11, s9, 0
	global_load_dwordx4 v[228:231], v246, s[10:11]
	global_load_dwordx4 v[238:241], v247, s[10:11]
	s_add_u32 s25, s25, 1
	s_and_b32 s0, s4, 7
	s_lshl_b32 s0, s0, 6
	s_mul_i32 s1, s17, 5184
	s_add_u32 s1, s1, s0
	s_add_u32 s1, s1, 0x5cbe240
	s_add_u32 s20, s50, s1
	s_addc_u32 s21, s51, 0
	s_lshl_b32 s1, s17, 11
	s_add_u32 s1, s1, s0
	s_add_u32 s1, s1, 0x18bd600
	s_add_u32 s14, s50, s1
	s_addc_u32 s15, s51, 0
	ds_read_b128 v[188:191], v248 offset:0
	ds_read_b128 v[192:195], v248 offset:32
	ds_read_b128 v[196:199], v248 offset:64
	ds_read_b128 v[200:203], v248 offset:96
	ds_read_b128 v[204:207], v248 offset:128
	ds_read_b128 v[208:211], v248 offset:160
	ds_read_b128 v[212:215], v248 offset:192
	ds_read_b128 v[216:219], v248 offset:224
	s_waitcnt vmcnt(6)
	s_waitcnt lgkmcnt(7)
	v_mfma_f32_32x32x16_bf16 v[0:15], v[188:191], v[48:51], v[144:159]
	ds_read_b128 v[188:191], v248 offset:256
	s_waitcnt lgkmcnt(7)
	v_mfma_f32_32x32x16_bf16 v[0:15], v[192:195], v[52:55], v[0:15]
	ds_read_b128 v[192:195], v248 offset:288
	s_waitcnt lgkmcnt(7)
	v_mfma_f32_32x32x16_bf16 v[0:15], v[196:199], v[56:59], v[0:15]
	ds_read_b128 v[196:199], v248 offset:320
	s_waitcnt lgkmcnt(7)
	v_mfma_f32_32x32x16_bf16 v[0:15], v[200:203], v[60:63], v[0:15]
	ds_read_b128 v[200:203], v248 offset:352
	s_waitcnt lgkmcnt(7)
	v_mfma_f32_32x32x16_bf16 v[0:15], v[204:207], v[64:67], v[0:15]
	ds_read_b128 v[204:207], v248 offset:384
	s_waitcnt lgkmcnt(7)
	v_mfma_f32_32x32x16_bf16 v[0:15], v[208:211], v[68:71], v[0:15]
	ds_read_b128 v[208:211], v248 offset:416
	s_waitcnt lgkmcnt(7)
	v_mfma_f32_32x32x16_bf16 v[0:15], v[212:215], v[72:75], v[0:15]
	ds_read_b128 v[212:215], v248 offset:448
	s_waitcnt lgkmcnt(7)
	v_mfma_f32_32x32x16_bf16 v[0:15], v[216:219], v[76:79], v[0:15]
	ds_read_b128 v[216:219], v248 offset:480
	s_waitcnt lgkmcnt(7)
	v_mfma_f32_32x32x16_bf16 v[0:15], v[188:191], v[96:99], v[0:15]
	s_waitcnt lgkmcnt(6)
	v_mfma_f32_32x32x16_bf16 v[0:15], v[192:195], v[100:103], v[0:15]
	s_waitcnt lgkmcnt(5)
	v_mfma_f32_32x32x16_bf16 v[0:15], v[196:199], v[104:107], v[0:15]
	s_waitcnt lgkmcnt(4)
	v_mfma_f32_32x32x16_bf16 v[0:15], v[200:203], v[108:111], v[0:15]
	s_waitcnt lgkmcnt(3)
	v_mfma_f32_32x32x16_bf16 v[0:15], v[204:207], v[112:115], v[0:15]
	s_waitcnt lgkmcnt(2)
	v_mfma_f32_32x32x16_bf16 v[0:15], v[208:211], v[116:119], v[0:15]
	s_waitcnt lgkmcnt(1)
	v_mfma_f32_32x32x16_bf16 v[0:15], v[212:215], v[120:123], v[0:15]
	s_waitcnt lgkmcnt(0)
	v_mfma_f32_32x32x16_bf16 v[0:15], v[216:219], v[124:127], v[0:15]
	s_add_u32 s0, s4, 1
	s_and_b32 s0, s0, 7
	s_lshl_b32 s0, s0, 7
	s_add_u32 s30, s22, s0
	s_addc_u32 s31, s23, 0
	global_load_dwordx4 v[144:147], v249, s[30:31] offset:0
	global_load_dwordx4 v[148:151], v249, s[30:31] offset:32
	global_load_dwordx4 v[152:155], v249, s[30:31] offset:64
	global_load_dwordx4 v[156:159], v249, s[30:31] offset:96
	global_load_dwordx4 v[160:163], v243, s[20:21]
	global_load_dwordx4 v[164:167], v243, s[20:21] offset:16
	s_cmp_eq_u32 s16, 0
	s_cbranch_scc0 .Lc_ep0
	global_load_dword v179, v249, s[22:23]
	global_load_dword v128, v249, s[22:23]
	s_branch .Lc_ex0
.Lc_ep0:
	s_waitcnt vmcnt(10)
	v_cvt_pk_bf16_f32 v130, v16, v17
	v_cvt_pk_bf16_f32 v131, v18, v19
	v_cvt_pk_bf16_f32 v134, v20, v21
	v_cvt_pk_bf16_f32 v135, v22, v23
	v_cvt_pk_bf16_f32 v132, v24, v25
	v_cvt_pk_bf16_f32 v133, v26, v27
	v_cvt_pk_bf16_f32 v136, v28, v29
	v_cvt_pk_bf16_f32 v137, v30, v31
	s_nop 1
	v_permlane32_swap_b32_e32 v130, v132
	v_permlane32_swap_b32_e32 v131, v133
	v_permlane32_swap_b32_e32 v134, v136
	v_permlane32_swap_b32_e32 v135, v137
	v_lshlrev_b32_e32 v138, 16, v170
	v_and_b32_e32 v139, 0xffff0000, v170
	v_lshlrev_b32_e32 v140, 16, v171
	v_and_b32_e32 v141, 0xffff0000, v171
	v_mul_f32_e32 v181, s65, v138
	v_mul_f32_e32 v182, s65, v139
	v_mul_f32_e32 v183, s65, v140
	v_mul_f32_e32 v184, s65, v141
	v_exp_f32_e32 v181, v181
	v_exp_f32_e32 v182, v182
	v_exp_f32_e32 v183, v183
	v_exp_f32_e32 v184, v184
	v_add_f32_e32 v181, 1.0, v181
	v_add_f32_e32 v182, 1.0, v182
	v_add_f32_e32 v183, 1.0, v183
	v_add_f32_e32 v184, 1.0, v184
	v_rcp_f32_e32 v181, v181
	v_rcp_f32_e32 v182, v182
	v_rcp_f32_e32 v183, v183
	v_rcp_f32_e32 v184, v184
	s_nop 0
	v_mul_f32_e32 v138, v138, v181
	v_mul_f32_e32 v139, v139, v182
	v_mul_f32_e32 v140, v140, v183
	v_mul_f32_e32 v141, v141, v184
	v_lshlrev_b32_e32 v181, 16, v130
	v_and_b32_e32 v182, 0xffff0000, v130
	v_lshlrev_b32_e32 v183, 16, v131
	v_and_b32_e32 v184, 0xffff0000, v131
	v_mul_f32_e32 v181, v181, v138
	v_mul_f32_e32 v182, v182, v139
	v_mul_f32_e32 v183, v183, v140
	v_mul_f32_e32 v184, v184, v141
	v_cvt_pk_bf16_f32 v130, v181, v182
	v_cvt_pk_bf16_f32 v131, v183, v184
	v_lshlrev_b32_e32 v138, 16, v172
	v_and_b32_e32 v139, 0xffff0000, v172
	v_lshlrev_b32_e32 v140, 16, v173
	v_and_b32_e32 v141, 0xffff0000, v173
	v_mul_f32_e32 v181, s65, v138
	v_mul_f32_e32 v182, s65, v139
	v_mul_f32_e32 v183, s65, v140
	v_mul_f32_e32 v184, s65, v141
	v_exp_f32_e32 v181, v181
	v_exp_f32_e32 v182, v182
	v_exp_f32_e32 v183, v183
	v_exp_f32_e32 v184, v184
	v_add_f32_e32 v181, 1.0, v181
	v_add_f32_e32 v182, 1.0, v182
	v_add_f32_e32 v183, 1.0, v183
	v_add_f32_e32 v184, 1.0, v184
	v_rcp_f32_e32 v181, v181
	v_rcp_f32_e32 v182, v182
	v_rcp_f32_e32 v183, v183
	v_rcp_f32_e32 v184, v184
	s_nop 0
	v_mul_f32_e32 v138, v138, v181
	v_mul_f32_e32 v139, v139, v182
	v_mul_f32_e32 v140, v140, v183
	v_mul_f32_e32 v141, v141, v184
	v_lshlrev_b32_e32 v181, 16, v132
	v_and_b32_e32 v182, 0xffff0000, v132
	v_lshlrev_b32_e32 v183, 16, v133
	v_and_b32_e32 v184, 0xffff0000, v133
	v_mul_f32_e32 v181, v181, v138
	v_mul_f32_e32 v182, v182, v139
	v_mul_f32_e32 v183, v183, v140
	v_mul_f32_e32 v184, v184, v141
	v_cvt_pk_bf16_f32 v132, v181, v182
	v_cvt_pk_bf16_f32 v133, v183, v184
	v_lshlrev_b32_e32 v138, 16, v174
	v_and_b32_e32 v139, 0xffff0000, v174
	v_lshlrev_b32_e32 v140, 16, v175
	v_and_b32_e32 v141, 0xffff0000, v175
	v_mul_f32_e32 v181, s65, v138
	v_mul_f32_e32 v182, s65, v139
	v_mul_f32_e32 v183, s65, v140
	v_mul_f32_e32 v184, s65, v141
	v_exp_f32_e32 v181, v181
	v_exp_f32_e32 v182, v182
	v_exp_f32_e32 v183, v183
	v_exp_f32_e32 v184, v184
	v_add_f32_e32 v181, 1.0, v181
	v_add_f32_e32 v182, 1.0, v182
	v_add_f32_e32 v183, 1.0, v183
	v_add_f32_e32 v184, 1.0, v184
	v_rcp_f32_e32 v181, v181
	v_rcp_f32_e32 v182, v182
	v_rcp_f32_e32 v183, v183
	v_rcp_f32_e32 v184, v184
	s_nop 0
	v_mul_f32_e32 v138, v138, v181
	v_mul_f32_e32 v139, v139, v182
	v_mul_f32_e32 v140, v140, v183
	v_mul_f32_e32 v141, v141, v184
	v_lshlrev_b32_e32 v181, 16, v134
	v_and_b32_e32 v182, 0xffff0000, v134
	v_lshlrev_b32_e32 v183, 16, v135
	v_and_b32_e32 v184, 0xffff0000, v135
	v_mul_f32_e32 v181, v181, v138
	v_mul_f32_e32 v182, v182, v139
	v_mul_f32_e32 v183, v183, v140
	v_mul_f32_e32 v184, v184, v141
	v_cvt_pk_bf16_f32 v134, v181, v182
	v_cvt_pk_bf16_f32 v135, v183, v184
	v_lshlrev_b32_e32 v138, 16, v176
	v_and_b32_e32 v139, 0xffff0000, v176
	v_lshlrev_b32_e32 v140, 16, v177
	v_and_b32_e32 v141, 0xffff0000, v177
	v_mul_f32_e32 v181, s65, v138
	v_mul_f32_e32 v182, s65, v139
	v_mul_f32_e32 v183, s65, v140
	v_mul_f32_e32 v184, s65, v141
	v_exp_f32_e32 v181, v181
	v_exp_f32_e32 v182, v182
	v_exp_f32_e32 v183, v183
	v_exp_f32_e32 v184, v184
	v_add_f32_e32 v181, 1.0, v181
	v_add_f32_e32 v182, 1.0, v182
	v_add_f32_e32 v183, 1.0, v183
	v_add_f32_e32 v184, 1.0, v184
	v_rcp_f32_e32 v181, v181
	v_rcp_f32_e32 v182, v182
	v_rcp_f32_e32 v183, v183
	v_rcp_f32_e32 v184, v184
	s_nop 0
	v_mul_f32_e32 v138, v138, v181
	v_mul_f32_e32 v139, v139, v182
	v_mul_f32_e32 v140, v140, v183
	v_mul_f32_e32 v141, v141, v184
	v_lshlrev_b32_e32 v181, 16, v136
	v_and_b32_e32 v182, 0xffff0000, v136
	v_lshlrev_b32_e32 v183, 16, v137
	v_and_b32_e32 v184, 0xffff0000, v137
	v_mul_f32_e32 v181, v181, v138
	v_mul_f32_e32 v182, v182, v139
	v_mul_f32_e32 v183, v183, v140
	v_mul_f32_e32 v184, v184, v141
	v_cvt_pk_bf16_f32 v136, v181, v182
	v_cvt_pk_bf16_f32 v137, v183, v184
	global_store_dwordx4 v244, v[130:133], s[12:13]
	global_store_dwordx4 v244, v[134:137], s[12:13] offset:16
.Lc_ex0:
	s_mov_b64 s[12:13], s[14:15]
	s_mov_b32 s16, 1
	s_add_u32 s4, s4, 1
	s_waitcnt lgkmcnt(0)
	s_barrier
	s_cmp_ge_u32 s4, s5
	s_cbranch_scc1 .Lc_drain0
	s_cmp_lg_u32 s4, s6
	s_cbranch_scc1 .Lc_ns0
	s_waitcnt vmcnt(0)
	s_nop 7
	s_nop 7
	v_cvt_pk_bf16_f32 v130, v0, v1
	v_cvt_pk_bf16_f32 v131, v2, v3
	v_cvt_pk_bf16_f32 v134, v4, v5
	v_cvt_pk_bf16_f32 v135, v6, v7
	v_cvt_pk_bf16_f32 v132, v8, v9
	v_cvt_pk_bf16_f32 v133, v10, v11
	v_cvt_pk_bf16_f32 v136, v12, v13
	v_cvt_pk_bf16_f32 v137, v14, v15
	s_nop 1
	v_permlane32_swap_b32_e32 v130, v132
	v_permlane32_swap_b32_e32 v131, v133
	v_permlane32_swap_b32_e32 v134, v136
	v_permlane32_swap_b32_e32 v135, v137
	v_lshlrev_b32_e32 v138, 16, v160
	v_and_b32_e32 v139, 0xffff0000, v160
	v_lshlrev_b32_e32 v140, 16, v161
	v_and_b32_e32 v141, 0xffff0000, v161
	v_mul_f32_e32 v181, s65, v138
	v_mul_f32_e32 v182, s65, v139
	v_mul_f32_e32 v183, s65, v140
	v_mul_f32_e32 v184, s65, v141
	v_exp_f32_e32 v181, v181
	v_exp_f32_e32 v182, v182
	v_exp_f32_e32 v183, v183
	v_exp_f32_e32 v184, v184
	v_add_f32_e32 v181, 1.0, v181
	v_add_f32_e32 v182, 1.0, v182
	v_add_f32_e32 v183, 1.0, v183
	v_add_f32_e32 v184, 1.0, v184
	v_rcp_f32_e32 v181, v181
	v_rcp_f32_e32 v182, v182
	v_rcp_f32_e32 v183, v183
	v_rcp_f32_e32 v184, v184
	s_nop 0
	v_mul_f32_e32 v138, v138, v181
	v_mul_f32_e32 v139, v139, v182
	v_mul_f32_e32 v140, v140, v183
	v_mul_f32_e32 v141, v141, v184
	v_lshlrev_b32_e32 v181, 16, v130
	v_and_b32_e32 v182, 0xffff0000, v130
	v_lshlrev_b32_e32 v183, 16, v131
	v_and_b32_e32 v184, 0xffff0000, v131
	v_mul_f32_e32 v181, v181, v138
	v_mul_f32_e32 v182, v182, v139
	v_mul_f32_e32 v183, v183, v140
	v_mul_f32_e32 v184, v184, v141
	v_cvt_pk_bf16_f32 v130, v181, v182
	v_cvt_pk_bf16_f32 v131, v183, v184
	v_lshlrev_b32_e32 v138, 16, v162
	v_and_b32_e32 v139, 0xffff0000, v162
	v_lshlrev_b32_e32 v140, 16, v163
	v_and_b32_e32 v141, 0xffff0000, v163
	v_mul_f32_e32 v181, s65, v138
	v_mul_f32_e32 v182, s65, v139
	v_mul_f32_e32 v183, s65, v140
	v_mul_f32_e32 v184, s65, v141
	v_exp_f32_e32 v181, v181
	v_exp_f32_e32 v182, v182
	v_exp_f32_e32 v183, v183
	v_exp_f32_e32 v184, v184
	v_add_f32_e32 v181, 1.0, v181
	v_add_f32_e32 v182, 1.0, v182
	v_add_f32_e32 v183, 1.0, v183
	v_add_f32_e32 v184, 1.0, v184
	v_rcp_f32_e32 v181, v181
	v_rcp_f32_e32 v182, v182
	v_rcp_f32_e32 v183, v183
	v_rcp_f32_e32 v184, v184
	s_nop 0
	v_mul_f32_e32 v138, v138, v181
	v_mul_f32_e32 v139, v139, v182
	v_mul_f32_e32 v140, v140, v183
	v_mul_f32_e32 v141, v141, v184
	v_lshlrev_b32_e32 v181, 16, v132
	v_and_b32_e32 v182, 0xffff0000, v132
	v_lshlrev_b32_e32 v183, 16, v133
	v_and_b32_e32 v184, 0xffff0000, v133
	v_mul_f32_e32 v181, v181, v138
	v_mul_f32_e32 v182, v182, v139
	v_mul_f32_e32 v183, v183, v140
	v_mul_f32_e32 v184, v184, v141
	v_cvt_pk_bf16_f32 v132, v181, v182
	v_cvt_pk_bf16_f32 v133, v183, v184
	v_lshlrev_b32_e32 v138, 16, v164
	v_and_b32_e32 v139, 0xffff0000, v164
	v_lshlrev_b32_e32 v140, 16, v165
	v_and_b32_e32 v141, 0xffff0000, v165
	v_mul_f32_e32 v181, s65, v138
	v_mul_f32_e32 v182, s65, v139
	v_mul_f32_e32 v183, s65, v140
	v_mul_f32_e32 v184, s65, v141
	v_exp_f32_e32 v181, v181
	v_exp_f32_e32 v182, v182
	v_exp_f32_e32 v183, v183
	v_exp_f32_e32 v184, v184
	v_add_f32_e32 v181, 1.0, v181
	v_add_f32_e32 v182, 1.0, v182
	v_add_f32_e32 v183, 1.0, v183
	v_add_f32_e32 v184, 1.0, v184
	v_rcp_f32_e32 v181, v181
	v_rcp_f32_e32 v182, v182
	v_rcp_f32_e32 v183, v183
	v_rcp_f32_e32 v184, v184
	s_nop 0
	v_mul_f32_e32 v138, v138, v181
	v_mul_f32_e32 v139, v139, v182
	v_mul_f32_e32 v140, v140, v183
	v_mul_f32_e32 v141, v141, v184
	v_lshlrev_b32_e32 v181, 16, v134
	v_and_b32_e32 v182, 0xffff0000, v134
	v_lshlrev_b32_e32 v183, 16, v135
	v_and_b32_e32 v184, 0xffff0000, v135
	v_mul_f32_e32 v181, v181, v138
	v_mul_f32_e32 v182, v182, v139
	v_mul_f32_e32 v183, v183, v140
	v_mul_f32_e32 v184, v184, v141
	v_cvt_pk_bf16_f32 v134, v181, v182
	v_cvt_pk_bf16_f32 v135, v183, v184
	v_lshlrev_b32_e32 v138, 16, v166
	v_and_b32_e32 v139, 0xffff0000, v166
	v_lshlrev_b32_e32 v140, 16, v167
	v_and_b32_e32 v141, 0xffff0000, v167
	v_mul_f32_e32 v181, s65, v138
	v_mul_f32_e32 v182, s65, v139
	v_mul_f32_e32 v183, s65, v140
	v_mul_f32_e32 v184, s65, v141
	v_exp_f32_e32 v181, v181
	v_exp_f32_e32 v182, v182
	v_exp_f32_e32 v183, v183
	v_exp_f32_e32 v184, v184
	v_add_f32_e32 v181, 1.0, v181
	v_add_f32_e32 v182, 1.0, v182
	v_add_f32_e32 v183, 1.0, v183
	v_add_f32_e32 v184, 1.0, v184
	v_rcp_f32_e32 v181, v181
	v_rcp_f32_e32 v182, v182
	v_rcp_f32_e32 v183, v183
	v_rcp_f32_e32 v184, v184
	s_nop 0
	v_mul_f32_e32 v138, v138, v181
	v_mul_f32_e32 v139, v139, v182
	v_mul_f32_e32 v140, v140, v183
	v_mul_f32_e32 v141, v141, v184
	v_lshlrev_b32_e32 v181, 16, v136
	v_and_b32_e32 v182, 0xffff0000, v136
	v_lshlrev_b32_e32 v183, 16, v137
	v_and_b32_e32 v184, 0xffff0000, v137
	v_mul_f32_e32 v181, v181, v138
	v_mul_f32_e32 v182, v182, v139
	v_mul_f32_e32 v183, v183, v140
	v_mul_f32_e32 v184, v184, v141
	v_cvt_pk_bf16_f32 v136, v181, v182
	v_cvt_pk_bf16_f32 v137, v183, v184
	global_store_dwordx4 v244, v[130:133], s[12:13]
	global_store_dwordx4 v244, v[134:137], s[12:13] offset:16
	s_mov_b32 s16, 0
	s_mov_b32 s6, s5
	s_lshr_b32 s17, s4, 3
	s_lshl_b32 s17, s17, 8
	s_lshl_b32 s54, s17, 9
	s_add_u32 s54, s54, 0x1995d000
	s_add_u32 s26, s50, s54
	s_addc_u32 s27, s51, 0
	global_load_dwordx4 v[48:51], v242, s[26:27] offset:0
	global_load_dwordx4 v[52:55], v242, s[26:27] offset:32
	global_load_dwordx4 v[56:59], v242, s[26:27] offset:64
	global_load_dwordx4 v[60:63], v242, s[26:27] offset:96
	global_load_dwordx4 v[64:67], v242, s[26:27] offset:128
	global_load_dwordx4 v[68:71], v242, s[26:27] offset:160
	global_load_dwordx4 v[72:75], v242, s[26:27] offset:192
	global_load_dwordx4 v[76:79], v242, s[26:27] offset:224
	global_load_dwordx4 v[96:99], v242, s[26:27] offset:256
	global_load_dwordx4 v[100:103], v242, s[26:27] offset:288
	global_load_dwordx4 v[104:107], v242, s[26:27] offset:320
	global_load_dwordx4 v[108:111], v242, s[26:27] offset:352
	global_load_dwordx4 v[112:115], v242, s[26:27] offset:384
	global_load_dwordx4 v[116:119], v242, s[26:27] offset:416
	global_load_dwordx4 v[120:123], v242, s[26:27] offset:448
	global_load_dwordx4 v[124:127], v242, s[26:27] offset:480
	s_waitcnt vmcnt(0)
.Lc_ns0:
	s_waitcnt vmcnt(18)
	ds_write_b128 v245, v[220:223] offset:0
	ds_write_b128 v245, v[224:227] offset:8448
	s_add_u32 s0, s5, -1
	s_min_u32 s0, s25, s0
	s_and_b32 s0, s0, 7
	s_lshl_b32 s0, s0, 14
	s_add_u32 s10, s8, s0
	s_addc_u32 s11, s9, 0
	global_load_dwordx4 v[220:223], v246, s[10:11]
	global_load_dwordx4 v[224:227], v247, s[10:11]
	s_add_u32 s25, s25, 1
	s_and_b32 s0, s4, 7
	s_lshl_b32 s0, s0, 6
	s_mul_i32 s1, s17, 5184
	s_add_u32 s1, s1, s0
	s_add_u32 s1, s1, 0x5cbe240
	s_add_u32 s20, s50, s1
	s_addc_u32 s21, s51, 0
	s_lshl_b32 s1, s17, 11
	s_add_u32 s1, s1, s0
	s_add_u32 s1, s1, 0x18bd600
	s_add_u32 s14, s50, s1
	s_addc_u32 s15, s51, 0
	ds_read_b128 v[188:191], v248 offset:16896
	ds_read_b128 v[192:195], v248 offset:16928
	ds_read_b128 v[196:199], v248 offset:16960
	ds_read_b128 v[200:203], v248 offset:16992
	ds_read_b128 v[204:207], v248 offset:17024
	ds_read_b128 v[208:211], v248 offset:17056
	ds_read_b128 v[212:215], v248 offset:17088
	ds_read_b128 v[216:219], v248 offset:17120
	s_waitcnt vmcnt(6)
	s_waitcnt lgkmcnt(7)
	v_mfma_f32_32x32x16_bf16 v[16:31], v[188:191], v[48:51], v[144:159]
	ds_read_b128 v[188:191], v248 offset:17152
	s_waitcnt lgkmcnt(7)
	v_mfma_f32_32x32x16_bf16 v[16:31], v[192:195], v[52:55], v[16:31]
	ds_read_b128 v[192:195], v248 offset:17184
	s_waitcnt lgkmcnt(7)
	v_mfma_f32_32x32x16_bf16 v[16:31], v[196:199], v[56:59], v[16:31]
	ds_read_b128 v[196:199], v248 offset:17216
	s_waitcnt lgkmcnt(7)
	v_mfma_f32_32x32x16_bf16 v[16:31], v[200:203], v[60:63], v[16:31]
	ds_read_b128 v[200:203], v248 offset:17248
	s_waitcnt lgkmcnt(7)
	v_mfma_f32_32x32x16_bf16 v[16:31], v[204:207], v[64:67], v[16:31]
	ds_read_b128 v[204:207], v248 offset:17280
	s_waitcnt lgkmcnt(7)
	v_mfma_f32_32x32x16_bf16 v[16:31], v[208:211], v[68:71], v[16:31]
	ds_read_b128 v[208:211], v248 offset:17312
	s_waitcnt lgkmcnt(7)
	v_mfma_f32_32x32x16_bf16 v[16:31], v[212:215], v[72:75], v[16:31]
	ds_read_b128 v[212:215], v248 offset:17344
	s_waitcnt lgkmcnt(7)
	v_mfma_f32_32x32x16_bf16 v[16:31], v[216:219], v[76:79], v[16:31]
	ds_read_b128 v[216:219], v248 offset:17376
	s_waitcnt lgkmcnt(7)
	v_mfma_f32_32x32x16_bf16 v[16:31], v[188:191], v[96:99], v[16:31]
	s_waitcnt lgkmcnt(6)
	v_mfma_f32_32x32x16_bf16 v[16:31], v[192:195], v[100:103], v[16:31]
	s_waitcnt lgkmcnt(5)
	v_mfma_f32_32x32x16_bf16 v[16:31], v[196:199], v[104:107], v[16:31]
	s_waitcnt lgkmcnt(4)
	v_mfma_f32_32x32x16_bf16 v[16:31], v[200:203], v[108:111], v[16:31]
	s_waitcnt lgkmcnt(3)
	v_mfma_f32_32x32x16_bf16 v[16:31], v[204:207], v[112:115], v[16:31]
	s_waitcnt lgkmcnt(2)
	v_mfma_f32_32x32x16_bf16 v[16:31], v[208:211], v[116:119], v[16:31]
	s_waitcnt lgkmcnt(1)
	v_mfma_f32_32x32x16_bf16 v[16:31], v[212:215], v[120:123], v[16:31]
	s_waitcnt lgkmcnt(0)
	v_mfma_f32_32x32x16_bf16 v[16:31], v[216:219], v[124:127], v[16:31]
	s_add_u32 s0, s4, 1
	s_and_b32 s0, s0, 7
	s_lshl_b32 s0, s0, 7
	s_add_u32 s30, s22, s0
	s_addc_u32 s31, s23, 0
	global_load_dwordx4 v[144:147], v249, s[30:31] offset:0
	global_load_dwordx4 v[148:151], v249, s[30:31] offset:32
	global_load_dwordx4 v[152:155], v249, s[30:31] offset:64
	global_load_dwordx4 v[156:159], v249, s[30:31] offset:96
	global_load_dwordx4 v[170:173], v243, s[20:21]
	global_load_dwordx4 v[174:177], v243, s[20:21] offset:16
	s_cmp_eq_u32 s16, 0
	s_cbranch_scc0 .Lc_ep1
	global_load_dword v179, v249, s[22:23]
	global_load_dword v128, v249, s[22:23]
	s_branch .Lc_ex1
.Lc_ep1:
	s_waitcnt vmcnt(10)
	v_cvt_pk_bf16_f32 v130, v0, v1
	v_cvt_pk_bf16_f32 v131, v2, v3
	v_cvt_pk_bf16_f32 v134, v4, v5
	v_cvt_pk_bf16_f32 v135, v6, v7
	v_cvt_pk_bf16_f32 v132, v8, v9
	v_cvt_pk_bf16_f32 v133, v10, v11
	v_cvt_pk_bf16_f32 v136, v12, v13
	v_cvt_pk_bf16_f32 v137, v14, v15
	s_nop 1
	v_permlane32_swap_b32_e32 v130, v132
	v_permlane32_swap_b32_e32 v131, v133
	v_permlane32_swap_b32_e32 v134, v136
	v_permlane32_swap_b32_e32 v135, v137
	v_lshlrev_b32_e32 v138, 16, v160
	v_and_b32_e32 v139, 0xffff0000, v160
	v_lshlrev_b32_e32 v140, 16, v161
	v_and_b32_e32 v141, 0xffff0000, v161
	v_mul_f32_e32 v181, s65, v138
	v_mul_f32_e32 v182, s65, v139
	v_mul_f32_e32 v183, s65, v140
	v_mul_f32_e32 v184, s65, v141
	v_exp_f32_e32 v181, v181
	v_exp_f32_e32 v182, v182
	v_exp_f32_e32 v183, v183
	v_exp_f32_e32 v184, v184
	v_add_f32_e32 v181, 1.0, v181
	v_add_f32_e32 v182, 1.0, v182
	v_add_f32_e32 v183, 1.0, v183
	v_add_f32_e32 v184, 1.0, v184
	v_rcp_f32_e32 v181, v181
	v_rcp_f32_e32 v182, v182
	v_rcp_f32_e32 v183, v183
	v_rcp_f32_e32 v184, v184
	s_nop 0
	v_mul_f32_e32 v138, v138, v181
	v_mul_f32_e32 v139, v139, v182
	v_mul_f32_e32 v140, v140, v183
	v_mul_f32_e32 v141, v141, v184
	v_lshlrev_b32_e32 v181, 16, v130
	v_and_b32_e32 v182, 0xffff0000, v130
	v_lshlrev_b32_e32 v183, 16, v131
	v_and_b32_e32 v184, 0xffff0000, v131
	v_mul_f32_e32 v181, v181, v138
	v_mul_f32_e32 v182, v182, v139
	v_mul_f32_e32 v183, v183, v140
	v_mul_f32_e32 v184, v184, v141
	v_cvt_pk_bf16_f32 v130, v181, v182
	v_cvt_pk_bf16_f32 v131, v183, v184
	v_lshlrev_b32_e32 v138, 16, v162
	v_and_b32_e32 v139, 0xffff0000, v162
	v_lshlrev_b32_e32 v140, 16, v163
	v_and_b32_e32 v141, 0xffff0000, v163
	v_mul_f32_e32 v181, s65, v138
	v_mul_f32_e32 v182, s65, v139
	v_mul_f32_e32 v183, s65, v140
	v_mul_f32_e32 v184, s65, v141
	v_exp_f32_e32 v181, v181
	v_exp_f32_e32 v182, v182
	v_exp_f32_e32 v183, v183
	v_exp_f32_e32 v184, v184
	v_add_f32_e32 v181, 1.0, v181
	v_add_f32_e32 v182, 1.0, v182
	v_add_f32_e32 v183, 1.0, v183
	v_add_f32_e32 v184, 1.0, v184
	v_rcp_f32_e32 v181, v181
	v_rcp_f32_e32 v182, v182
	v_rcp_f32_e32 v183, v183
	v_rcp_f32_e32 v184, v184
	s_nop 0
	v_mul_f32_e32 v138, v138, v181
	v_mul_f32_e32 v139, v139, v182
	v_mul_f32_e32 v140, v140, v183
	v_mul_f32_e32 v141, v141, v184
	v_lshlrev_b32_e32 v181, 16, v132
	v_and_b32_e32 v182, 0xffff0000, v132
	v_lshlrev_b32_e32 v183, 16, v133
	v_and_b32_e32 v184, 0xffff0000, v133
	v_mul_f32_e32 v181, v181, v138
	v_mul_f32_e32 v182, v182, v139
	v_mul_f32_e32 v183, v183, v140
	v_mul_f32_e32 v184, v184, v141
	v_cvt_pk_bf16_f32 v132, v181, v182
	v_cvt_pk_bf16_f32 v133, v183, v184
	v_lshlrev_b32_e32 v138, 16, v164
	v_and_b32_e32 v139, 0xffff0000, v164
	v_lshlrev_b32_e32 v140, 16, v165
	v_and_b32_e32 v141, 0xffff0000, v165
	v_mul_f32_e32 v181, s65, v138
	v_mul_f32_e32 v182, s65, v139
	v_mul_f32_e32 v183, s65, v140
	v_mul_f32_e32 v184, s65, v141
	v_exp_f32_e32 v181, v181
	v_exp_f32_e32 v182, v182
	v_exp_f32_e32 v183, v183
	v_exp_f32_e32 v184, v184
	v_add_f32_e32 v181, 1.0, v181
	v_add_f32_e32 v182, 1.0, v182
	v_add_f32_e32 v183, 1.0, v183
	v_add_f32_e32 v184, 1.0, v184
	v_rcp_f32_e32 v181, v181
	v_rcp_f32_e32 v182, v182
	v_rcp_f32_e32 v183, v183
	v_rcp_f32_e32 v184, v184
	s_nop 0
	v_mul_f32_e32 v138, v138, v181
	v_mul_f32_e32 v139, v139, v182
	v_mul_f32_e32 v140, v140, v183
	v_mul_f32_e32 v141, v141, v184
	v_lshlrev_b32_e32 v181, 16, v134
	v_and_b32_e32 v182, 0xffff0000, v134
	v_lshlrev_b32_e32 v183, 16, v135
	v_and_b32_e32 v184, 0xffff0000, v135
	v_mul_f32_e32 v181, v181, v138
	v_mul_f32_e32 v182, v182, v139
	v_mul_f32_e32 v183, v183, v140
	v_mul_f32_e32 v184, v184, v141
	v_cvt_pk_bf16_f32 v134, v181, v182
	v_cvt_pk_bf16_f32 v135, v183, v184
	v_lshlrev_b32_e32 v138, 16, v166
	v_and_b32_e32 v139, 0xffff0000, v166
	v_lshlrev_b32_e32 v140, 16, v167
	v_and_b32_e32 v141, 0xffff0000, v167
	v_mul_f32_e32 v181, s65, v138
	v_mul_f32_e32 v182, s65, v139
	v_mul_f32_e32 v183, s65, v140
	v_mul_f32_e32 v184, s65, v141
	v_exp_f32_e32 v181, v181
	v_exp_f32_e32 v182, v182
	v_exp_f32_e32 v183, v183
	v_exp_f32_e32 v184, v184
	v_add_f32_e32 v181, 1.0, v181
	v_add_f32_e32 v182, 1.0, v182
	v_add_f32_e32 v183, 1.0, v183
	v_add_f32_e32 v184, 1.0, v184
	v_rcp_f32_e32 v181, v181
	v_rcp_f32_e32 v182, v182
	v_rcp_f32_e32 v183, v183
	v_rcp_f32_e32 v184, v184
	s_nop 0
	v_mul_f32_e32 v138, v138, v181
	v_mul_f32_e32 v139, v139, v182
	v_mul_f32_e32 v140, v140, v183
	v_mul_f32_e32 v141, v141, v184
	v_lshlrev_b32_e32 v181, 16, v136
	v_and_b32_e32 v182, 0xffff0000, v136
	v_lshlrev_b32_e32 v183, 16, v137
	v_and_b32_e32 v184, 0xffff0000, v137
	v_mul_f32_e32 v181, v181, v138
	v_mul_f32_e32 v182, v182, v139
	v_mul_f32_e32 v183, v183, v140
	v_mul_f32_e32 v184, v184, v141
	v_cvt_pk_bf16_f32 v136, v181, v182
	v_cvt_pk_bf16_f32 v137, v183, v184
	global_store_dwordx4 v244, v[130:133], s[12:13]
	global_store_dwordx4 v244, v[134:137], s[12:13] offset:16
.Lc_ex1:
	s_mov_b64 s[12:13], s[14:15]
	s_mov_b32 s16, 1
	s_add_u32 s4, s4, 1
	s_waitcnt lgkmcnt(0)
	s_barrier
	s_cmp_ge_u32 s4, s5
	s_cbranch_scc1 .Lc_drain1
	s_cmp_lg_u32 s4, s6
	s_cbranch_scc1 .Lc_ns1
	s_waitcnt vmcnt(0)
	s_nop 7
	s_nop 7
	v_cvt_pk_bf16_f32 v130, v16, v17
	v_cvt_pk_bf16_f32 v131, v18, v19
	v_cvt_pk_bf16_f32 v134, v20, v21
	v_cvt_pk_bf16_f32 v135, v22, v23
	v_cvt_pk_bf16_f32 v132, v24, v25
	v_cvt_pk_bf16_f32 v133, v26, v27
	v_cvt_pk_bf16_f32 v136, v28, v29
	v_cvt_pk_bf16_f32 v137, v30, v31
	s_nop 1
	v_permlane32_swap_b32_e32 v130, v132
	v_permlane32_swap_b32_e32 v131, v133
	v_permlane32_swap_b32_e32 v134, v136
	v_permlane32_swap_b32_e32 v135, v137
	v_lshlrev_b32_e32 v138, 16, v170
	v_and_b32_e32 v139, 0xffff0000, v170
	v_lshlrev_b32_e32 v140, 16, v171
	v_and_b32_e32 v141, 0xffff0000, v171
	v_mul_f32_e32 v181, s65, v138
	v_mul_f32_e32 v182, s65, v139
	v_mul_f32_e32 v183, s65, v140
	v_mul_f32_e32 v184, s65, v141
	v_exp_f32_e32 v181, v181
	v_exp_f32_e32 v182, v182
	v_exp_f32_e32 v183, v183
	v_exp_f32_e32 v184, v184
	v_add_f32_e32 v181, 1.0, v181
	v_add_f32_e32 v182, 1.0, v182
	v_add_f32_e32 v183, 1.0, v183
	v_add_f32_e32 v184, 1.0, v184
	v_rcp_f32_e32 v181, v181
	v_rcp_f32_e32 v182, v182
	v_rcp_f32_e32 v183, v183
	v_rcp_f32_e32 v184, v184
	s_nop 0
	v_mul_f32_e32 v138, v138, v181
	v_mul_f32_e32 v139, v139, v182
	v_mul_f32_e32 v140, v140, v183
	v_mul_f32_e32 v141, v141, v184
	v_lshlrev_b32_e32 v181, 16, v130
	v_and_b32_e32 v182, 0xffff0000, v130
	v_lshlrev_b32_e32 v183, 16, v131
	v_and_b32_e32 v184, 0xffff0000, v131
	v_mul_f32_e32 v181, v181, v138
	v_mul_f32_e32 v182, v182, v139
	v_mul_f32_e32 v183, v183, v140
	v_mul_f32_e32 v184, v184, v141
	v_cvt_pk_bf16_f32 v130, v181, v182
	v_cvt_pk_bf16_f32 v131, v183, v184
	v_lshlrev_b32_e32 v138, 16, v172
	v_and_b32_e32 v139, 0xffff0000, v172
	v_lshlrev_b32_e32 v140, 16, v173
	v_and_b32_e32 v141, 0xffff0000, v173
	v_mul_f32_e32 v181, s65, v138
	v_mul_f32_e32 v182, s65, v139
	v_mul_f32_e32 v183, s65, v140
	v_mul_f32_e32 v184, s65, v141
	v_exp_f32_e32 v181, v181
	v_exp_f32_e32 v182, v182
	v_exp_f32_e32 v183, v183
	v_exp_f32_e32 v184, v184
	v_add_f32_e32 v181, 1.0, v181
	v_add_f32_e32 v182, 1.0, v182
	v_add_f32_e32 v183, 1.0, v183
	v_add_f32_e32 v184, 1.0, v184
	v_rcp_f32_e32 v181, v181
	v_rcp_f32_e32 v182, v182
	v_rcp_f32_e32 v183, v183
	v_rcp_f32_e32 v184, v184
	s_nop 0
	v_mul_f32_e32 v138, v138, v181
	v_mul_f32_e32 v139, v139, v182
	v_mul_f32_e32 v140, v140, v183
	v_mul_f32_e32 v141, v141, v184
	v_lshlrev_b32_e32 v181, 16, v132
	v_and_b32_e32 v182, 0xffff0000, v132
	v_lshlrev_b32_e32 v183, 16, v133
	v_and_b32_e32 v184, 0xffff0000, v133
	v_mul_f32_e32 v181, v181, v138
	v_mul_f32_e32 v182, v182, v139
	v_mul_f32_e32 v183, v183, v140
	v_mul_f32_e32 v184, v184, v141
	v_cvt_pk_bf16_f32 v132, v181, v182
	v_cvt_pk_bf16_f32 v133, v183, v184
	v_lshlrev_b32_e32 v138, 16, v174
	v_and_b32_e32 v139, 0xffff0000, v174
	v_lshlrev_b32_e32 v140, 16, v175
	v_and_b32_e32 v141, 0xffff0000, v175
	v_mul_f32_e32 v181, s65, v138
	v_mul_f32_e32 v182, s65, v139
	v_mul_f32_e32 v183, s65, v140
	v_mul_f32_e32 v184, s65, v141
	v_exp_f32_e32 v181, v181
	v_exp_f32_e32 v182, v182
	v_exp_f32_e32 v183, v183
	v_exp_f32_e32 v184, v184
	v_add_f32_e32 v181, 1.0, v181
	v_add_f32_e32 v182, 1.0, v182
	v_add_f32_e32 v183, 1.0, v183
	v_add_f32_e32 v184, 1.0, v184
	v_rcp_f32_e32 v181, v181
	v_rcp_f32_e32 v182, v182
	v_rcp_f32_e32 v183, v183
	v_rcp_f32_e32 v184, v184
	s_nop 0
	v_mul_f32_e32 v138, v138, v181
	v_mul_f32_e32 v139, v139, v182
	v_mul_f32_e32 v140, v140, v183
	v_mul_f32_e32 v141, v141, v184
	v_lshlrev_b32_e32 v181, 16, v134
	v_and_b32_e32 v182, 0xffff0000, v134
	v_lshlrev_b32_e32 v183, 16, v135
	v_and_b32_e32 v184, 0xffff0000, v135
	v_mul_f32_e32 v181, v181, v138
	v_mul_f32_e32 v182, v182, v139
	v_mul_f32_e32 v183, v183, v140
	v_mul_f32_e32 v184, v184, v141
	v_cvt_pk_bf16_f32 v134, v181, v182
	v_cvt_pk_bf16_f32 v135, v183, v184
	v_lshlrev_b32_e32 v138, 16, v176
	v_and_b32_e32 v139, 0xffff0000, v176
	v_lshlrev_b32_e32 v140, 16, v177
	v_and_b32_e32 v141, 0xffff0000, v177
	v_mul_f32_e32 v181, s65, v138
	v_mul_f32_e32 v182, s65, v139
	v_mul_f32_e32 v183, s65, v140
	v_mul_f32_e32 v184, s65, v141
	v_exp_f32_e32 v181, v181
	v_exp_f32_e32 v182, v182
	v_exp_f32_e32 v183, v183
	v_exp_f32_e32 v184, v184
	v_add_f32_e32 v181, 1.0, v181
	v_add_f32_e32 v182, 1.0, v182
	v_add_f32_e32 v183, 1.0, v183
	v_add_f32_e32 v184, 1.0, v184
	v_rcp_f32_e32 v181, v181
	v_rcp_f32_e32 v182, v182
	v_rcp_f32_e32 v183, v183
	v_rcp_f32_e32 v184, v184
	s_nop 0
	v_mul_f32_e32 v138, v138, v181
	v_mul_f32_e32 v139, v139, v182
	v_mul_f32_e32 v140, v140, v183
	v_mul_f32_e32 v141, v141, v184
	v_lshlrev_b32_e32 v181, 16, v136
	v_and_b32_e32 v182, 0xffff0000, v136
	v_lshlrev_b32_e32 v183, 16, v137
	v_and_b32_e32 v184, 0xffff0000, v137
	v_mul_f32_e32 v181, v181, v138
	v_mul_f32_e32 v182, v182, v139
	v_mul_f32_e32 v183, v183, v140
	v_mul_f32_e32 v184, v184, v141
	v_cvt_pk_bf16_f32 v136, v181, v182
	v_cvt_pk_bf16_f32 v137, v183, v184
	global_store_dwordx4 v244, v[130:133], s[12:13]
	global_store_dwordx4 v244, v[134:137], s[12:13] offset:16
	s_mov_b32 s16, 0
	s_mov_b32 s6, s5
	s_lshr_b32 s17, s4, 3
	s_lshl_b32 s17, s17, 8
	s_lshl_b32 s54, s17, 9
	s_add_u32 s54, s54, 0x1995d000
	s_add_u32 s26, s50, s54
	s_addc_u32 s27, s51, 0
	global_load_dwordx4 v[48:51], v242, s[26:27] offset:0
	global_load_dwordx4 v[52:55], v242, s[26:27] offset:32
	global_load_dwordx4 v[56:59], v242, s[26:27] offset:64
	global_load_dwordx4 v[60:63], v242, s[26:27] offset:96
	global_load_dwordx4 v[64:67], v242, s[26:27] offset:128
	global_load_dwordx4 v[68:71], v242, s[26:27] offset:160
	global_load_dwordx4 v[72:75], v242, s[26:27] offset:192
	global_load_dwordx4 v[76:79], v242, s[26:27] offset:224
	global_load_dwordx4 v[96:99], v242, s[26:27] offset:256
	global_load_dwordx4 v[100:103], v242, s[26:27] offset:288
	global_load_dwordx4 v[104:107], v242, s[26:27] offset:320
	global_load_dwordx4 v[108:111], v242, s[26:27] offset:352
	global_load_dwordx4 v[112:115], v242, s[26:27] offset:384
	global_load_dwordx4 v[116:119], v242, s[26:27] offset:416
	global_load_dwordx4 v[120:123], v242, s[26:27] offset:448
	global_load_dwordx4 v[124:127], v242, s[26:27] offset:480
	s_waitcnt vmcnt(0)

.Lc_drain0:
	s_waitcnt vmcnt(0)
	s_nop 7
	s_nop 7
	v_cvt_pk_bf16_f32 v130, v0, v1
	v_cvt_pk_bf16_f32 v131, v2, v3
	v_cvt_pk_bf16_f32 v134, v4, v5
	v_cvt_pk_bf16_f32 v135, v6, v7
	v_cvt_pk_bf16_f32 v132, v8, v9
	v_cvt_pk_bf16_f32 v133, v10, v11
	v_cvt_pk_bf16_f32 v136, v12, v13
	v_cvt_pk_bf16_f32 v137, v14, v15
	s_nop 1
	v_permlane32_swap_b32_e32 v130, v132
	v_permlane32_swap_b32_e32 v131, v133
	v_permlane32_swap_b32_e32 v134, v136
	v_permlane32_swap_b32_e32 v135, v137
	v_lshlrev_b32_e32 v138, 16, v160
	v_and_b32_e32 v139, 0xffff0000, v160
	v_lshlrev_b32_e32 v140, 16, v161
	v_and_b32_e32 v141, 0xffff0000, v161
	v_mul_f32_e32 v181, s65, v138
	v_mul_f32_e32 v182, s65, v139
	v_mul_f32_e32 v183, s65, v140
	v_mul_f32_e32 v184, s65, v141
	v_exp_f32_e32 v181, v181
	v_exp_f32_e32 v182, v182
	v_exp_f32_e32 v183, v183
	v_exp_f32_e32 v184, v184
	v_add_f32_e32 v181, 1.0, v181
	v_add_f32_e32 v182, 1.0, v182
	v_add_f32_e32 v183, 1.0, v183
	v_add_f32_e32 v184, 1.0, v184
	v_rcp_f32_e32 v181, v181
	v_rcp_f32_e32 v182, v182
	v_rcp_f32_e32 v183, v183
	v_rcp_f32_e32 v184, v184
	s_nop 0
	v_mul_f32_e32 v138, v138, v181
	v_mul_f32_e32 v139, v139, v182
	v_mul_f32_e32 v140, v140, v183
	v_mul_f32_e32 v141, v141, v184
	v_lshlrev_b32_e32 v181, 16, v130
	v_and_b32_e32 v182, 0xffff0000, v130
	v_lshlrev_b32_e32 v183, 16, v131
	v_and_b32_e32 v184, 0xffff0000, v131
	v_mul_f32_e32 v181, v181, v138
	v_mul_f32_e32 v182, v182, v139
	v_mul_f32_e32 v183, v183, v140
	v_mul_f32_e32 v184, v184, v141
	v_cvt_pk_bf16_f32 v130, v181, v182
	v_cvt_pk_bf16_f32 v131, v183, v184
	v_lshlrev_b32_e32 v138, 16, v162
	v_and_b32_e32 v139, 0xffff0000, v162
	v_lshlrev_b32_e32 v140, 16, v163
	v_and_b32_e32 v141, 0xffff0000, v163
	v_mul_f32_e32 v181, s65, v138
	v_mul_f32_e32 v182, s65, v139
	v_mul_f32_e32 v183, s65, v140
	v_mul_f32_e32 v184, s65, v141
	v_exp_f32_e32 v181, v181
	v_exp_f32_e32 v182, v182
	v_exp_f32_e32 v183, v183
	v_exp_f32_e32 v184, v184
	v_add_f32_e32 v181, 1.0, v181
	v_add_f32_e32 v182, 1.0, v182
	v_add_f32_e32 v183, 1.0, v183
	v_add_f32_e32 v184, 1.0, v184
	v_rcp_f32_e32 v181, v181
	v_rcp_f32_e32 v182, v182
	v_rcp_f32_e32 v183, v183
	v_rcp_f32_e32 v184, v184
	s_nop 0
	v_mul_f32_e32 v138, v138, v181
	v_mul_f32_e32 v139, v139, v182
	v_mul_f32_e32 v140, v140, v183
	v_mul_f32_e32 v141, v141, v184
	v_lshlrev_b32_e32 v181, 16, v132
	v_and_b32_e32 v182, 0xffff0000, v132
	v_lshlrev_b32_e32 v183, 16, v133
	v_and_b32_e32 v184, 0xffff0000, v133
	v_mul_f32_e32 v181, v181, v138
	v_mul_f32_e32 v182, v182, v139
	v_mul_f32_e32 v183, v183, v140
	v_mul_f32_e32 v184, v184, v141
	v_cvt_pk_bf16_f32 v132, v181, v182
	v_cvt_pk_bf16_f32 v133, v183, v184
	v_lshlrev_b32_e32 v138, 16, v164
	v_and_b32_e32 v139, 0xffff0000, v164
	v_lshlrev_b32_e32 v140, 16, v165
	v_and_b32_e32 v141, 0xffff0000, v165
	v_mul_f32_e32 v181, s65, v138
	v_mul_f32_e32 v182, s65, v139
	v_mul_f32_e32 v183, s65, v140
	v_mul_f32_e32 v184, s65, v141
	v_exp_f32_e32 v181, v181
	v_exp_f32_e32 v182, v182
	v_exp_f32_e32 v183, v183
	v_exp_f32_e32 v184, v184
	v_add_f32_e32 v181, 1.0, v181
	v_add_f32_e32 v182, 1.0, v182
	v_add_f32_e32 v183, 1.0, v183
	v_add_f32_e32 v184, 1.0, v184
	v_rcp_f32_e32 v181, v181
	v_rcp_f32_e32 v182, v182
	v_rcp_f32_e32 v183, v183
	v_rcp_f32_e32 v184, v184
	s_nop 0
	v_mul_f32_e32 v138, v138, v181
	v_mul_f32_e32 v139, v139, v182
	v_mul_f32_e32 v140, v140, v183
	v_mul_f32_e32 v141, v141, v184
	v_lshlrev_b32_e32 v181, 16, v134
	v_and_b32_e32 v182, 0xffff0000, v134
	v_lshlrev_b32_e32 v183, 16, v135
	v_and_b32_e32 v184, 0xffff0000, v135
	v_mul_f32_e32 v181, v181, v138
	v_mul_f32_e32 v182, v182, v139
	v_mul_f32_e32 v183, v183, v140
	v_mul_f32_e32 v184, v184, v141
	v_cvt_pk_bf16_f32 v134, v181, v182
	v_cvt_pk_bf16_f32 v135, v183, v184
	v_lshlrev_b32_e32 v138, 16, v166
	v_and_b32_e32 v139, 0xffff0000, v166
	v_lshlrev_b32_e32 v140, 16, v167
	v_and_b32_e32 v141, 0xffff0000, v167
	v_mul_f32_e32 v181, s65, v138
	v_mul_f32_e32 v182, s65, v139
	v_mul_f32_e32 v183, s65, v140
	v_mul_f32_e32 v184, s65, v141
	v_exp_f32_e32 v181, v181
	v_exp_f32_e32 v182, v182
	v_exp_f32_e32 v183, v183
	v_exp_f32_e32 v184, v184
	v_add_f32_e32 v181, 1.0, v181
	v_add_f32_e32 v182, 1.0, v182
	v_add_f32_e32 v183, 1.0, v183
	v_add_f32_e32 v184, 1.0, v184
	v_rcp_f32_e32 v181, v181
	v_rcp_f32_e32 v182, v182
	v_rcp_f32_e32 v183, v183
	v_rcp_f32_e32 v184, v184
	s_nop 0
	v_mul_f32_e32 v138, v138, v181
	v_mul_f32_e32 v139, v139, v182
	v_mul_f32_e32 v140, v140, v183
	v_mul_f32_e32 v141, v141, v184
	v_lshlrev_b32_e32 v181, 16, v136
	v_and_b32_e32 v182, 0xffff0000, v136
	v_lshlrev_b32_e32 v183, 16, v137
	v_and_b32_e32 v184, 0xffff0000, v137
	v_mul_f32_e32 v181, v181, v138
	v_mul_f32_e32 v182, v182, v139
	v_mul_f32_e32 v183, v183, v140
	v_mul_f32_e32 v184, v184, v141
	v_cvt_pk_bf16_f32 v136, v181, v182
	v_cvt_pk_bf16_f32 v137, v183, v184
	global_store_dwordx4 v244, v[130:133], s[12:13]
	global_store_dwordx4 v244, v[134:137], s[12:13] offset:16
	s_branch .Lc_done
.Lc_drain1:
	s_waitcnt vmcnt(0)
	s_nop 7
	s_nop 7
	v_cvt_pk_bf16_f32 v130, v16, v17
	v_cvt_pk_bf16_f32 v131, v18, v19
	v_cvt_pk_bf16_f32 v134, v20, v21
	v_cvt_pk_bf16_f32 v135, v22, v23
	v_cvt_pk_bf16_f32 v132, v24, v25
	v_cvt_pk_bf16_f32 v133, v26, v27
	v_cvt_pk_bf16_f32 v136, v28, v29
	v_cvt_pk_bf16_f32 v137, v30, v31
	s_nop 1
	v_permlane32_swap_b32_e32 v130, v132
	v_permlane32_swap_b32_e32 v131, v133
	v_permlane32_swap_b32_e32 v134, v136
	v_permlane32_swap_b32_e32 v135, v137
	v_lshlrev_b32_e32 v138, 16, v170
	v_and_b32_e32 v139, 0xffff0000, v170
	v_lshlrev_b32_e32 v140, 16, v171
	v_and_b32_e32 v141, 0xffff0000, v171
	v_mul_f32_e32 v181, s65, v138
	v_mul_f32_e32 v182, s65, v139
	v_mul_f32_e32 v183, s65, v140
	v_mul_f32_e32 v184, s65, v141
	v_exp_f32_e32 v181, v181
	v_exp_f32_e32 v182, v182
	v_exp_f32_e32 v183, v183
	v_exp_f32_e32 v184, v184
	v_add_f32_e32 v181, 1.0, v181
	v_add_f32_e32 v182, 1.0, v182
	v_add_f32_e32 v183, 1.0, v183
	v_add_f32_e32 v184, 1.0, v184
	v_rcp_f32_e32 v181, v181
	v_rcp_f32_e32 v182, v182
	v_rcp_f32_e32 v183, v183
	v_rcp_f32_e32 v184, v184
	s_nop 0
	v_mul_f32_e32 v138, v138, v181
	v_mul_f32_e32 v139, v139, v182
	v_mul_f32_e32 v140, v140, v183
	v_mul_f32_e32 v141, v141, v184
	v_lshlrev_b32_e32 v181, 16, v130
	v_and_b32_e32 v182, 0xffff0000, v130
	v_lshlrev_b32_e32 v183, 16, v131
	v_and_b32_e32 v184, 0xffff0000, v131
	v_mul_f32_e32 v181, v181, v138
	v_mul_f32_e32 v182, v182, v139
	v_mul_f32_e32 v183, v183, v140
	v_mul_f32_e32 v184, v184, v141
	v_cvt_pk_bf16_f32 v130, v181, v182
	v_cvt_pk_bf16_f32 v131, v183, v184
	v_lshlrev_b32_e32 v138, 16, v172
	v_and_b32_e32 v139, 0xffff0000, v172
	v_lshlrev_b32_e32 v140, 16, v173
	v_and_b32_e32 v141, 0xffff0000, v173
	v_mul_f32_e32 v181, s65, v138
	v_mul_f32_e32 v182, s65, v139
	v_mul_f32_e32 v183, s65, v140
	v_mul_f32_e32 v184, s65, v141
	v_exp_f32_e32 v181, v181
	v_exp_f32_e32 v182, v182
	v_exp_f32_e32 v183, v183
	v_exp_f32_e32 v184, v184
	v_add_f32_e32 v181, 1.0, v181
	v_add_f32_e32 v182, 1.0, v182
	v_add_f32_e32 v183, 1.0, v183
	v_add_f32_e32 v184, 1.0, v184
	v_rcp_f32_e32 v181, v181
	v_rcp_f32_e32 v182, v182
	v_rcp_f32_e32 v183, v183
	v_rcp_f32_e32 v184, v184
	s_nop 0
	v_mul_f32_e32 v138, v138, v181
	v_mul_f32_e32 v139, v139, v182
	v_mul_f32_e32 v140, v140, v183
	v_mul_f32_e32 v141, v141, v184
	v_lshlrev_b32_e32 v181, 16, v132
	v_and_b32_e32 v182, 0xffff0000, v132
	v_lshlrev_b32_e32 v183, 16, v133
	v_and_b32_e32 v184, 0xffff0000, v133
	v_mul_f32_e32 v181, v181, v138
	v_mul_f32_e32 v182, v182, v139
	v_mul_f32_e32 v183, v183, v140
	v_mul_f32_e32 v184, v184, v141
	v_cvt_pk_bf16_f32 v132, v181, v182
	v_cvt_pk_bf16_f32 v133, v183, v184
	v_lshlrev_b32_e32 v138, 16, v174
	v_and_b32_e32 v139, 0xffff0000, v174
	v_lshlrev_b32_e32 v140, 16, v175
	v_and_b32_e32 v141, 0xffff0000, v175
	v_mul_f32_e32 v181, s65, v138
	v_mul_f32_e32 v182, s65, v139
	v_mul_f32_e32 v183, s65, v140
	v_mul_f32_e32 v184, s65, v141
	v_exp_f32_e32 v181, v181
	v_exp_f32_e32 v182, v182
	v_exp_f32_e32 v183, v183
	v_exp_f32_e32 v184, v184
	v_add_f32_e32 v181, 1.0, v181
	v_add_f32_e32 v182, 1.0, v182
	v_add_f32_e32 v183, 1.0, v183
	v_add_f32_e32 v184, 1.0, v184
	v_rcp_f32_e32 v181, v181
	v_rcp_f32_e32 v182, v182
	v_rcp_f32_e32 v183, v183
	v_rcp_f32_e32 v184, v184
	s_nop 0
	v_mul_f32_e32 v138, v138, v181
	v_mul_f32_e32 v139, v139, v182
	v_mul_f32_e32 v140, v140, v183
	v_mul_f32_e32 v141, v141, v184
	v_lshlrev_b32_e32 v181, 16, v134
	v_and_b32_e32 v182, 0xffff0000, v134
	v_lshlrev_b32_e32 v183, 16, v135
	v_and_b32_e32 v184, 0xffff0000, v135
	v_mul_f32_e32 v181, v181, v138
	v_mul_f32_e32 v182, v182, v139
	v_mul_f32_e32 v183, v183, v140
	v_mul_f32_e32 v184, v184, v141
	v_cvt_pk_bf16_f32 v134, v181, v182
	v_cvt_pk_bf16_f32 v135, v183, v184
	v_lshlrev_b32_e32 v138, 16, v176
	v_and_b32_e32 v139, 0xffff0000, v176
	v_lshlrev_b32_e32 v140, 16, v177
	v_and_b32_e32 v141, 0xffff0000, v177
	v_mul_f32_e32 v181, s65, v138
	v_mul_f32_e32 v182, s65, v139
	v_mul_f32_e32 v183, s65, v140
	v_mul_f32_e32 v184, s65, v141
	v_exp_f32_e32 v181, v181
	v_exp_f32_e32 v182, v182
	v_exp_f32_e32 v183, v183
	v_exp_f32_e32 v184, v184
	v_add_f32_e32 v181, 1.0, v181
	v_add_f32_e32 v182, 1.0, v182
	v_add_f32_e32 v183, 1.0, v183
	v_add_f32_e32 v184, 1.0, v184
	v_rcp_f32_e32 v181, v181
	v_rcp_f32_e32 v182, v182
	v_rcp_f32_e32 v183, v183
	v_rcp_f32_e32 v184, v184
	s_nop 0
	v_mul_f32_e32 v138, v138, v181
	v_mul_f32_e32 v139, v139, v182
	v_mul_f32_e32 v140, v140, v183
	v_mul_f32_e32 v141, v141, v184
	v_lshlrev_b32_e32 v181, 16, v136
	v_and_b32_e32 v182, 0xffff0000, v136
	v_lshlrev_b32_e32 v183, 16, v137
	v_and_b32_e32 v184, 0xffff0000, v137
	v_mul_f32_e32 v181, v181, v138
	v_mul_f32_e32 v182, v182, v139
	v_mul_f32_e32 v183, v183, v140
	v_mul_f32_e32 v184, v184, v141
	v_cvt_pk_bf16_f32 v136, v181, v182
	v_cvt_pk_bf16_f32 v137, v183, v184
	global_store_dwordx4 v244, v[130:133], s[12:13]
	global_store_dwordx4 v244, v[134:137], s[12:13] offset:16
	s_branch .Lc_done
.Lc_done:
	s_waitcnt vmcnt(0)
	v_mov_b32_e32 v0, v143
	s_and_b64 vcc, exec, s[72:73]
	s_mov_b32 s75, s97
	s_branch .LBB0_870
	s_cbranch_vccz .LBB0_419
	v_readlane_b32 s4, v255, 23
	s_mov_b32 s1, 0
	s_mov_b32 s0, 0
	v_readlane_b32 s16, v253, 0
	v_readlane_b32 s5, v255, 24
	s_mov_b32 s17, s4
	s_branch .LBB0_420
